# GEMM phase prologues: second K-tile's LDS-DMA loads issued with the first tile's, first wait counted vmcnt(10) (on v15)
# speedup vs baseline: 1.0045x; 1.0045x over previous
; #define G_STAGE_A(buf, h, b0, b1, tt) do { const bool _s2 = P::SEG && (tt) >= P::TS; \
;         const char* _g = _s2 ? (b1) + (ptrdiff_t)((tt) - P::TS) * kA2 + (ptrdiff_t)(h) * hA2 : (b0) + (ptrdiff_t)(tt) * kA + (ptrdiff_t)(h) * hA; \
;         stage2(lds + G_SA(buf, h) + ldsw, _g, _s2 ? voA20 : voA0, _s2 ? voA21 : voA1); } while (0)
; #define G_STAGE_B(buf, h, b0, b1, tt) do { const bool _s2 = P::SEG && (tt) >= P::TS; \
;         const char* _g = _s2 ? (b1) + (ptrdiff_t)((tt) - P::TS) * kB2 + (ptrdiff_t)(h) * hB2 : (b0) + (ptrdiff_t)(tt) * kB + (ptrdiff_t)(h) * hB; \
;         stage2(lds + G_SB(buf, h) + ldsw, _g, _s2 ? voB20 : voB0, _s2 ? voB21 : voB1); } while (0)
; #define G_WAIT_V(n) asm volatile("s_waitcnt vmcnt(" #n ")" ::: "memory")
; #define G_BAR __builtin_amdgcn_s_barrier()
;     __device__ __forceinline__ int voffA(int R, int C) const { return (R * LDA + C) * 2; }
;     __device__ __forceinline__ int voffB(int R, int C) const { return (R * LDB + C) * 2; }
;     __device__ __forceinline__ int voffA(int R, int C) const { return (R * D + C) * 2; }
;     __device__ __forceinline__ int voffB(int R, int C) const { return (((R >> 4) - (C >> 4)) * 256 + (R & 15) * 16 + (C & 15)) * 2; }
;     __device__ __forceinline__ int voffA2(int R, int C) const { return (R * 256 + C) * 2; }
;     __device__ __forceinline__ int voffB2(int R, int C) const { return (R * 256 + C) * 2; }
;     ...
;     { int R, C; stage_rc(tid * 16, R, C); int Rb = P::PERM ? ((R & ~31) + perm32(R & 31)) : R; voA0 = p.voffA(R, C); voB0 = p.voffB(Rb, C);
;       if constexpr (P::SEG) { voA20 = p.voffA2(R, C); voB20 = p.voffB2(Rb, C); } }
;     { int R, C; stage_rc(tid * 16 + 8192, R, C); int Rb = P::PERM ? ((R & ~31) + perm32(R & 31)) : R; voA1 = p.voffA(R, C); voB1 = p.voffB(Rb, C);
;       if constexpr (P::SEG) { voA21 = p.voffA2(R, C); voB21 = p.voffB2(Rb, C); } }
;     ...
;     const char* cA = p.a0(cur); const char* cB = p.b0(cur);
;     const char* cA2 = P::SEG ? p.a1(cur) : cA; const char* cB2 = P::SEG ? p.b1(cur) : cB;
;     G_STAGE_B(0, 0, cB, cB2, 0); G_STAGE_A(0, 0, cA, cA2, 0); G_STAGE_B(0, 1, cB, cB2, 0); G_STAGE_A(0, 1, cA, cA2, 0);
;     if (wr == 1) G_BAR;
;     G_WAIT_V(4); G_BAR;
;     G_STAGE_B(1, 0, cB, cB2, 1); G_STAGE_A(1, 0, cA, cA2, 1); G_STAGE_B(1, 1, cB, cB2, 1);
;     G_WAIT_V(6); G_BAR;
.LBB0_226:
	v_lshlrev_b32_e32 v0, 4, v9
	v_add_u32_e32 v1, 0x2000, v0
	v_ashrrev_i32_e32 v2, 31, v1
	v_lshrrev_b32_e32 v2, 22, v2
	v_add_u32_e32 v2, v1, v2
	v_ashrrev_i32_e32 v8, 10, v2
	v_mul_i32_i24_e32 v2, 0x400, v8
	v_sub_u32_e32 v1, v1, v2
	v_lshrrev_b32_e32 v2, 4, v1
	v_bitop3_b32 v1, v2, v1, 32 bitop3:0x6c
	v_ashrrev_i32_e32 v2, 31, v1
	v_lshrrev_b32_e32 v2, 26, v2
	v_add_u32_e32 v2, v1, v2
	v_lshlrev_b32_e32 v3, 3, v8
	v_ashrrev_i32_e32 v10, 6, v2
	v_and_b32_e32 v3, -16, v3
	v_add_u32_e32 v3, v10, v3
	v_and_b32_e32 v4, 3, v10
	s_mov_b32 s6, 0x1fffe0
	v_lshrrev_b32_e32 v5, 2, v3
	v_lshlrev_b32_e32 v6, 1, v3
	v_and_b32_e32 v2, 0xc0, v2
	v_and_or_b32 v4, v3, s6, v4
	v_and_b32_e32 v5, 4, v5
	v_and_b32_e32 v6, 24, v6
	v_sub_u32_e32 v1, v1, v2
	v_mov_b32_e32 v2, 1
	v_or3_b32 v4, v4, v5, v6
	v_lshlrev_b32_e32 v5, 5, v8
	v_ashrrev_i16_sdwa v1, v2, sext(v1) dst_sel:DWORD dst_unused:UNUSED_PAD src0_sel:DWORD src1_sel:BYTE_0
	v_and_b32_e32 v5, 32, v5
	v_bfe_i32 v11, v1, 0, 16
	v_add_lshl_u32 v1, v5, v11, 1
	v_lshl_add_u32 v130, v4, 11, v1
	v_lshl_add_u32 v132, v3, 11, v1
	v_bfe_i32 v1, v9, 27, 1
	v_lshrrev_b32_e32 v1, 22, v1
	v_add_u32_e32 v1, v0, v1
	v_and_b32_e32 v1, 0xfffffc00, v1
	v_sub_u32_e32 v0, v0, v1
	v_lshrrev_b32_e32 v1, 4, v0
	v_bitop3_b32 v1, v1, v0, 32 bitop3:0x6c
	v_ashrrev_i32_e32 v0, 31, v0
	v_lshrrev_b32_e32 v0, 26, v0
	v_add_u32_e32 v0, v1, v0
	v_ashrrev_i32_e32 v12, 6, v0
	v_ashrrev_i32_e32 v0, 31, v9
	v_lshrrev_b32_e32 v0, 26, v0
	v_add_u32_e32 v0, v9, v0
	v_ashrrev_i32_e32 v13, 6, v0
	v_lshlrev_b32_e32 v0, 3, v13
	v_and_b32_e32 v0, -16, v0
	s_add_u32 s39, s10, 0xf000000
	v_add_u32_e32 v0, v12, v0
	v_and_b32_e32 v3, 3, v12
	s_addc_u32 s40, s11, 0
	v_and_or_b32 v3, v0, s6, v3
	s_ashr_i32 s6, s33, 31
	s_lshr_b32 s6, s6, 29
	s_add_i32 s6, s33, s6
	s_ashr_i32 s7, s6, 3
	s_and_b32 s6, s6, -8
	s_sub_i32 s6, s33, s6
	s_lshr_b32 s8, s6, 31
	s_or_b32 s8, s8, 0x160
	s_mul_i32 s6, s8, s6
	v_lshrrev_b32_e32 v4, 2, v0
	v_lshlrev_b32_e32 v5, 1, v0
	s_add_i32 s6, s6, s7
	v_and_b32_e32 v4, 4, v4
	v_and_b32_e32 v5, 24, v5
	s_mul_hi_i32 s7, s6, 0x2e8ba2e9
	v_or3_b32 v3, v3, v4, v5
	v_mul_i32_i24_e32 v5, 64, v12
	s_lshr_b32 s8, s7, 31
	s_ashr_i32 s7, s7, 5
	v_sub_u32_e32 v1, v1, v5
	s_add_i32 s7, s7, s8
	v_lshlrev_b32_e32 v4, 5, v13
	v_ashrrev_i16_sdwa v1, v2, sext(v1) dst_sel:DWORD dst_unused:UNUSED_PAD src0_sel:DWORD src1_sel:BYTE_0
	s_lshl_b32 s9, s7, 3
	v_and_b32_e32 v4, 32, v4
	v_bfe_i32 v14, v1, 0, 16
	s_sub_i32 s8, 0x80, s9
	v_add_lshl_u32 v1, v4, v14, 1
	s_min_u32 s12, s8, 8
	s_mulk_i32 s7, 0xb0
	v_lshl_add_u32 v134, v3, 11, v1
	s_sub_i32 s13, s6, s7
	v_cvt_f32_ubyte0_e32 v3, s12
	v_cvt_f32_i32_e32 v2, s13
	v_rcp_iflag_f32_e32 v4, v3
	v_lshl_add_u32 v136, v0, 11, v1
	s_ashr_i32 s3, s38, 6
	s_ashr_i32 s6, s13, 30
	v_mul_f32_e32 v0, v2, v4
	v_trunc_f32_e32 v0, v0
	v_fma_f32 v1, -v0, v3, v2
	v_cvt_i32_f32_e32 v0, v0
	s_ashr_i32 s2, s38, 8
	s_lshl_b32 s14, s3, 10
	s_or_b32 s8, s6, 1
	v_cmp_ge_f32_e64 s[6:7], |v1|, v3
	s_and_b64 s[6:7], s[6:7], exec
	s_cselect_b32 s6, s8, 0
	v_readfirstlane_b32 s7, v0
	s_add_i32 s8, s7, s6
	s_mul_i32 s6, s8, s12
	s_sub_i32 s6, s13, s6
	s_sext_i32_i16 s6, s6
	s_add_i32 s24, s9, s6
	s_ashr_i32 s25, s24, 31
	s_lshl_b64 s[6:7], s[24:25], 19
	s_add_u32 s26, s10, s6
	s_addc_u32 s27, s11, s7
	s_bfe_i64 s[6:7], s[8:9], 0x100000
	s_lshl_b64 s[6:7], s[6:7], 19
	s_add_u32 s28, s39, s6
	s_addc_u32 s29, s40, s7
	s_add_i32 s25, s14, 0
	v_ashrrev_i32_e32 v135, 31, v134
	s_add_i32 m0, s25, 0x10000
	v_lshl_add_u64 v[0:1], s[28:29], 0, v[134:135]
	v_ashrrev_i32_e32 v131, 31, v130
	global_load_lds_dwordx4 v[0:1], off
	v_lshl_add_u64 v[2:3], s[28:29], 0, v[130:131]
	s_add_i32 m0, s25, 0x12000
	v_ashrrev_i32_e32 v137, 31, v136
	s_add_i32 s41, s25, 0x2000
	global_load_lds_dwordx4 v[2:3], off
	v_lshl_add_u64 v[4:5], s[26:27], 0, v[136:137]
	s_mov_b32 m0, s25
	v_ashrrev_i32_e32 v133, 31, v132
	s_add_u32 s6, s28, 0x40000
	global_load_lds_dwordx4 v[4:5], off
	v_lshl_add_u64 v[6:7], s[26:27], 0, v[132:133]
	s_mov_b32 m0, s41
	s_addc_u32 s7, s29, 0
	global_load_lds_dwordx4 v[6:7], off
	s_add_i32 m0, s25, 0x14000
	v_lshl_add_u64 v[16:17], s[6:7], 0, v[134:135]
	global_load_lds_dwordx4 v[16:17], off
	s_add_i32 m0, s25, 0x16000
	v_lshl_add_u64 v[16:17], s[6:7], 0, v[130:131]
	s_add_u32 s6, s26, 0x40000
	s_addc_u32 s7, s27, 0
	s_add_i32 s42, s25, 0x4000
	global_load_lds_dwordx4 v[16:17], off
	v_lshl_add_u64 v[16:17], s[6:7], 0, v[136:137]
	s_mov_b32 m0, s42
	s_add_i32 s43, s25, 0x6000
	global_load_lds_dwordx4 v[16:17], off
	v_lshl_add_u64 v[16:17], s[6:7], 0, v[132:133]
	s_mov_b32 m0, s43
	global_load_lds_dwordx4 v[16:17], off
	s_mov_b64 s[6:7], 0x80
	s_add_i32 m0, s25, 0x18000
	v_lshl_add_u64 v[0:1], v[0:1], 0, s[6:7]
	global_load_lds_dwordx4 v[0:1], off
	v_lshl_add_u64 v[0:1], v[2:3], 0, s[6:7]
	s_add_i32 m0, s25, 0x1a000
	s_add_i32 s44, s25, 0x8000
	s_add_i32 s45, s25, 0xa000
	global_load_lds_dwordx4 v[0:1], off
	v_lshl_add_u64 v[0:1], v[4:5], 0, s[6:7]
	s_mov_b32 m0, s44
	s_add_u32 s12, s28, 0x40080
	global_load_lds_dwordx4 v[0:1], off
	v_lshl_add_u64 v[0:1], v[6:7], 0, s[6:7]
	s_mov_b32 m0, s45
	s_addc_u32 s13, s29, 0
	global_load_lds_dwordx4 v[0:1], off
	s_add_i32 m0, s25, 0x1c000
	v_lshl_add_u64 v[0:1], s[12:13], 0, v[134:135]
	global_load_lds_dwordx4 v[0:1], off
	v_lshl_add_u64 v[0:1], s[12:13], 0, v[130:131]
	s_add_i32 m0, s25, 0x1e000
	v_lshlrev_b32_e32 v3, 2, v9
	global_load_lds_dwordx4 v[0:1], off
	s_cmp_lg_u32 s2, 1
	s_cbranch_scc1 .LBB0_228
	s_barrier
; #define G_STAGE_A(buf, h, b0, b1, tt) do { const bool _s2 = P::SEG && (tt) >= P::TS; \
;         const char* _g = _s2 ? (b1) + (ptrdiff_t)((tt) - P::TS) * kA2 + (ptrdiff_t)(h) * hA2 : (b0) + (ptrdiff_t)(tt) * kA + (ptrdiff_t)(h) * hA; \
;         stage2(lds + G_SA(buf, h) + ldsw, _g, _s2 ? voA20 : voA0, _s2 ? voA21 : voA1); } while (0)
; #define G_STAGE_B(buf, h, b0, b1, tt) do { const bool _s2 = P::SEG && (tt) >= P::TS; \
;         const char* _g = _s2 ? (b1) + (ptrdiff_t)((tt) - P::TS) * kB2 + (ptrdiff_t)(h) * hB2 : (b0) + (ptrdiff_t)(tt) * kB + (ptrdiff_t)(h) * hB; \
;         stage2(lds + G_SB(buf, h) + ldsw, _g, _s2 ? voB20 : voB0, _s2 ? voB21 : voB1); } while (0)
; #define G_WAIT_V(n) asm volatile("s_waitcnt vmcnt(" #n ")" ::: "memory")
; #define G_BAR __builtin_amdgcn_s_barrier()
;     ...
;     const unsigned ldsw = (unsigned)wid * 1024u;
;     const int aoff = lds_byte(wr * 64 + fr, fq * 8), boff = lds_byte(wc * 32 + fr, fq * 8);
;     ...
;     G_WAIT_V(4); G_BAR;
;     G_STAGE_B(1, 0, cB, cB2, 1); G_STAGE_A(1, 0, cA, cA2, 1); G_STAGE_B(1, 1, cB, cB2, 1);
;     G_WAIT_V(6); G_BAR;
.LBB0_228:
	s_and_b32 s9, s3, 3
	s_lshl_b32 s15, s2, 6
	s_lshl_b32 s16, s2, 13
	s_lshl_b32 s17, s9, 12
	s_add_u32 s2, s10, 0x4000000
	s_addc_u32 s3, s11, 0
	s_waitcnt vmcnt(10)
	s_barrier
	v_bfe_u32 v1, v9, 4, 2
	v_lshlrev_b32_e32 v2, 3, v1
	v_and_b32_e32 v0, 15, v9
	v_lshlrev_b32_e32 v1, 4, v1
	v_lshl_or_b32 v150, s9, 5, v2
	v_mov_b32_e32 v2, 0xcf
	v_or_b32_e32 v129, s15, v0
	v_lshl_or_b32 v1, v0, 6, v1
	v_bitop3_b32 v151, s15, v2, v0 bitop3:0xc8
	v_lshlrev_b32_e32 v0, 14, v13
	v_and_b32_e32 v0, 0xffff8000, v0
	v_lshl_add_u32 v0, v12, 11, v0
	v_and_b32_e32 v2, 1, v13
	v_lshl_or_b32 v0, v2, 6, v0
	v_lshl_add_u32 v138, v14, 1, v0
	v_lshlrev_b32_e32 v0, 14, v8
	v_and_b32_e32 v0, 0xffff8000, v0
	v_and_b32_e32 v3, 32, v3
	v_lshl_add_u32 v0, v10, 11, v0
	v_and_b32_e32 v2, 1, v8
	v_bitop3_b32 v4, v1, s16, v3 bitop3:0xde
	v_bitop3_b32 v1, v1, s17, v3 bitop3:0xde
	s_waitcnt vmcnt(6)
	v_lshl_or_b32 v0, v2, 6, v0
	s_add_i32 s49, 0, 0x10000
	s_add_i32 s55, 0, 0x14000
	s_add_i32 s57, 0, 0x18000
	v_lshl_add_u32 v140, v11, 1, v0
	v_add_u32_e32 v152, s49, v1
	v_add_u32_e32 v154, s55, v1
	s_add_i32 s49, s49, s14
	s_add_i32 s55, s55, s14
	v_add_u32_e32 v155, s57, v1
	s_add_i32 s59, 0, 0x1c000
	s_add_i32 s57, s57, s14
	s_sext_i32_i16 s60, s8
	s_mov_b32 s46, 0
	v_ashrrev_i32_e32 v139, 31, v138
	v_ashrrev_i32_e32 v141, 31, v140
	v_add_u32_e32 v153, 0, v4
	s_add_i32 s47, s25, 0xc000
	s_add_i32 s48, s25, 0xe000
	s_mov_b64 s[8:9], 0x100
	s_add_i32 s50, s49, 0x2000
	s_mov_b64 s[12:13], 0x180
	s_movk_i32 s51, 0x1600
	s_movk_i32 s52, 0xdf
	s_movk_i32 s53, 0xef
	s_movk_i32 s54, 0xff
	s_add_i32 s56, s55, 0x2000
	v_add_u32_e32 v156, s59, v1
	s_add_i32 s58, s57, 0x2000
	s_add_i32 s59, s59, s14
	s_barrier

; #define G_STAGE_A(buf, h, b0, b1, tt) do { const bool _s2 = P::SEG && (tt) >= P::TS; \
;         const char* _g = _s2 ? (b1) + (ptrdiff_t)((tt) - P::TS) * kA2 + (ptrdiff_t)(h) * hA2 : (b0) + (ptrdiff_t)(tt) * kA + (ptrdiff_t)(h) * hA; \
;         stage2(lds + G_SA(buf, h) + ldsw, _g, _s2 ? voA20 : voA0, _s2 ? voA21 : voA1); } while (0)
; #define G_STAGE_B(buf, h, b0, b1, tt) do { const bool _s2 = P::SEG && (tt) >= P::TS; \
;         const char* _g = _s2 ? (b1) + (ptrdiff_t)((tt) - P::TS) * kB2 + (ptrdiff_t)(h) * hB2 : (b0) + (ptrdiff_t)(tt) * kB + (ptrdiff_t)(h) * hB; \
;         stage2(lds + G_SB(buf, h) + ldsw, _g, _s2 ? voB20 : voB0, _s2 ? voB21 : voB1); } while (0)
; #define G_WAIT_V(n) asm volatile("s_waitcnt vmcnt(" #n ")" ::: "memory")
; #define G_BAR __builtin_amdgcn_s_barrier()
;     __device__ __forceinline__ int voffA(int R, int C) const { return (R * LDA + C) * 2; }
;     __device__ __forceinline__ int voffB(int R, int C) const { return (R * LDB + C) * 2; }
;     __device__ __forceinline__ int voffA(int R, int C) const { return (R * D + C) * 2; }
;     __device__ __forceinline__ int voffB(int R, int C) const { return (((R >> 4) - (C >> 4)) * 256 + (R & 15) * 16 + (C & 15)) * 2; }
;     __device__ __forceinline__ int voffA2(int R, int C) const { return (R * 256 + C) * 2; }
;     __device__ __forceinline__ int voffB2(int R, int C) const { return (R * 256 + C) * 2; }
;     ...
;     { int R, C; stage_rc(tid * 16, R, C); int Rb = P::PERM ? ((R & ~31) + perm32(R & 31)) : R; voA0 = p.voffA(R, C); voB0 = p.voffB(Rb, C);
;       if constexpr (P::SEG) { voA20 = p.voffA2(R, C); voB20 = p.voffB2(Rb, C); } }
;     { int R, C; stage_rc(tid * 16 + 8192, R, C); int Rb = P::PERM ? ((R & ~31) + perm32(R & 31)) : R; voA1 = p.voffA(R, C); voB1 = p.voffB(Rb, C);
;       if constexpr (P::SEG) { voA21 = p.voffA2(R, C); voB21 = p.voffB2(Rb, C); } }
;     ...
;     const char* cA = p.a0(cur); const char* cB = p.b0(cur);
;     const char* cA2 = P::SEG ? p.a1(cur) : cA; const char* cB2 = P::SEG ? p.b1(cur) : cB;
;     G_STAGE_B(0, 0, cB, cB2, 0); G_STAGE_A(0, 0, cA, cA2, 0); G_STAGE_B(0, 1, cB, cB2, 0); G_STAGE_A(0, 1, cA, cA2, 0);
;     if (wr == 1) G_BAR;
;     G_WAIT_V(4); G_BAR;
;     G_STAGE_B(1, 0, cB, cB2, 1); G_STAGE_A(1, 0, cA, cA2, 1); G_STAGE_B(1, 1, cB, cB2, 1);
;     G_WAIT_V(6); G_BAR;
.LBB0_346:
	v_ashrrev_i32_e32 v1, 31, v8
	v_lshrrev_b32_e32 v1, 26, v1
	v_add_u32_e32 v1, v8, v1
	v_ashrrev_i32_e32 v9, 6, v1
	v_bfe_i32 v1, v8, 27, 1
	v_lshlrev_b32_e32 v0, 4, v8
	v_lshrrev_b32_e32 v1, 22, v1
	v_add_u32_e32 v1, v0, v1
	v_and_b32_e32 v1, 0xfffffc00, v1
	v_sub_u32_e32 v1, v0, v1
	v_lshrrev_b32_e32 v2, 4, v1
	v_bitop3_b32 v2, v2, v1, 32 bitop3:0x6c
	v_ashrrev_i32_e32 v1, 31, v1
	v_lshrrev_b32_e32 v1, 26, v1
	v_lshlrev_b32_e32 v3, 3, v9
	v_add_u32_e32 v1, v2, v1
	v_and_b32_e32 v3, -16, v3
	v_ashrrev_i32_e32 v11, 6, v1
	v_add_u32_e32 v1, v11, v3
	v_lshlrev_b32_e32 v3, 5, v9
	v_and_b32_e32 v10, 32, v3
	v_mul_i32_i24_e32 v3, 64, v11
	v_sub_u32_e32 v2, v2, v3
	v_mov_b32_e32 v3, 1
	v_ashrrev_i16_sdwa v2, v3, sext(v2) dst_sel:DWORD dst_unused:UNUSED_PAD src0_sel:DWORD src1_sel:BYTE_0
	v_lshlrev_b32_e32 v4, 1, v1
	v_lshrrev_b32_e32 v5, 2, v1
	v_and_b32_e32 v6, 3, v11
	s_mov_b32 s1, 0xffffe0
	v_bfe_i32 v12, v2, 0, 16
	v_and_b32_e32 v4, 24, v4
	v_and_b32_e32 v5, 4, v5
	v_and_or_b32 v6, v1, s1, v6
	s_movk_i32 s8, 0xb00
	v_add_u32_e32 v2, v10, v12
	v_or3_b32 v4, v6, v5, v4
	v_mul_lo_u32 v1, v1, s8
	v_add_lshl_u32 v154, v2, v1, 1
	v_mul_u32_u24_e32 v1, 0xb00, v4
	v_add_u32_e32 v0, 0x2000, v0
	v_add_lshl_u32 v156, v1, v2, 1
	v_ashrrev_i32_e32 v1, 31, v0
	v_lshrrev_b32_e32 v1, 22, v1
	v_add_u32_e32 v1, v0, v1
	v_ashrrev_i32_e32 v13, 10, v1
	v_mul_i32_i24_e32 v1, 0x400, v13
	v_sub_u32_e32 v0, v0, v1
	v_lshrrev_b32_e32 v1, 4, v0
	v_bitop3_b32 v0, v1, v0, 32 bitop3:0x6c
	v_ashrrev_i32_e32 v2, 31, v0
	s_add_u32 s41, s20, 0xfb00000
	v_lshrrev_b32_e32 v2, 26, v2
	s_addc_u32 s42, s21, 0
	s_ashr_i32 s2, s39, 6
	v_lshlrev_b32_e32 v1, 3, v13
	v_add_u32_e32 v2, v0, v2
	s_ashr_i32 s0, s39, 8
	v_and_b32_e32 v1, -16, v1
	v_ashrrev_i32_e32 v14, 6, v2
	v_and_b32_e32 v2, 0xc0, v2
	s_lshl_b32 s43, s2, 10
	v_add_u32_e32 v1, v14, v1
	v_lshlrev_b32_e32 v4, 5, v13
	v_sub_u32_e32 v0, v0, v2
	s_add_u32 s44, s20, 0x4000000
	v_and_b32_e32 v15, 32, v4
	v_ashrrev_i16_sdwa v0, v3, sext(v0) dst_sel:DWORD dst_unused:UNUSED_PAD src0_sel:DWORD src1_sel:BYTE_0
	v_lshlrev_b32_e32 v2, 1, v1
	v_lshrrev_b32_e32 v3, 2, v1
	v_and_b32_e32 v4, 3, v14
	s_addc_u32 s45, s21, 0
	s_mul_i32 s3, s61, 0x160000
	v_bfe_i32 v16, v0, 0, 16
	v_and_b32_e32 v2, 24, v2
	v_and_b32_e32 v3, 4, v3
	v_and_or_b32 v4, v1, s1, v4
	s_mul_hi_i32 s1, s61, 0x160000
	s_add_u32 s28, s44, s3
	v_add_u32_e32 v0, v15, v16
	v_or3_b32 v2, v4, v3, v2
	v_mul_lo_u32 v1, v1, s8
	s_addc_u32 s29, s45, s1
	s_mul_i32 s3, s40, 0x160000
	v_add_lshl_u32 v158, v0, v1, 1
	v_mul_u32_u24_e32 v1, 0xb00, v2
	s_mul_hi_i32 s1, s40, 0x160000
	s_add_u32 s30, s41, s3
	v_add_lshl_u32 v160, v1, v0, 1
	s_addc_u32 s31, s42, s1
	s_add_i32 s46, s43, 0
	v_ashrrev_i32_e32 v157, 31, v156
	s_add_i32 m0, s46, 0x10000
	v_lshl_add_u64 v[0:1], s[30:31], 0, v[156:157]
	v_ashrrev_i32_e32 v161, 31, v160
	global_load_lds_dwordx4 v[0:1], off
	v_lshl_add_u64 v[2:3], s[30:31], 0, v[160:161]
	s_add_i32 m0, s46, 0x12000
	v_ashrrev_i32_e32 v155, 31, v154
	s_add_i32 s47, s46, 0x2000
	global_load_lds_dwordx4 v[2:3], off
	v_lshl_add_u64 v[4:5], s[28:29], 0, v[154:155]
	s_mov_b32 m0, s46
	v_ashrrev_i32_e32 v159, 31, v158
	s_add_u32 s6, s30, 0xb0000
	global_load_lds_dwordx4 v[4:5], off
	v_lshl_add_u64 v[6:7], s[28:29], 0, v[158:159]
	s_mov_b32 m0, s47
	s_addc_u32 s7, s31, 0
	global_load_lds_dwordx4 v[6:7], off
	s_add_i32 m0, s46, 0x14000
	v_lshl_add_u64 v[18:19], s[6:7], 0, v[156:157]
	global_load_lds_dwordx4 v[18:19], off
	s_add_i32 m0, s46, 0x16000
	v_lshl_add_u64 v[18:19], s[6:7], 0, v[160:161]
	s_add_u32 s6, s28, 0xb0000
	s_addc_u32 s7, s29, 0
	s_add_i32 s48, s46, 0x4000
	global_load_lds_dwordx4 v[18:19], off
	v_lshl_add_u64 v[18:19], s[6:7], 0, v[154:155]
	s_mov_b32 m0, s48
	s_add_i32 s49, s46, 0x6000
	global_load_lds_dwordx4 v[18:19], off
	v_lshl_add_u64 v[18:19], s[6:7], 0, v[158:159]
	s_mov_b32 m0, s49
	global_load_lds_dwordx4 v[18:19], off
	s_mov_b32 s1, 0
	s_mov_b64 s[10:11], 0x80
	s_add_i32 m0, s46, 0x18000
	v_lshl_add_u64 v[0:1], v[0:1], 0, s[10:11]
	global_load_lds_dwordx4 v[0:1], off
	v_lshl_add_u64 v[0:1], v[2:3], 0, s[10:11]
	s_add_i32 m0, s46, 0x1a000
	s_add_i32 s51, s46, 0x8000
	s_add_i32 s52, s46, 0xa000
	global_load_lds_dwordx4 v[0:1], off
	v_lshl_add_u64 v[0:1], v[4:5], 0, s[10:11]
	s_mov_b32 m0, s51
	s_add_u32 s6, s30, 0xb0080
	global_load_lds_dwordx4 v[0:1], off
	v_lshl_add_u64 v[0:1], v[6:7], 0, s[10:11]
	s_mov_b32 m0, s52
	s_addc_u32 s7, s31, 0
	global_load_lds_dwordx4 v[0:1], off
	s_add_i32 m0, s46, 0x1c000
	v_lshl_add_u64 v[0:1], s[6:7], 0, v[156:157]
	global_load_lds_dwordx4 v[0:1], off
	v_lshl_add_u64 v[0:1], s[6:7], 0, v[160:161]
	s_add_i32 m0, s46, 0x1e000
	s_add_i32 s56, 0, 0x10000
	global_load_lds_dwordx4 v[0:1], off
	s_cmp_lg_u32 s0, 1
	s_cbranch_scc1 .LBB0_348
	s_barrier
.LBB0_348:
	s_and_b32 s50, s2, 3
	s_lshl_b32 s9, s0, 13
	s_lshl_b32 s12, s50, 12
	s_add_u32 s2, s20, 0x10500000
	s_addc_u32 s3, s21, 0
	s_waitcnt vmcnt(10)
	s_barrier
	v_bfe_u32 v1, v8, 4, 2
	v_and_b32_e32 v0, 15, v8
	v_lshlrev_b32_e32 v3, 4, v1
	v_lshl_or_b32 v153, s0, 6, v0
	v_lshl_or_b32 v0, v0, 6, v3
	v_lshlrev_b32_e32 v3, 2, v8
	v_and_b32_e32 v3, 32, v3
	v_lshlrev_b32_e32 v2, 3, v1
	v_bitop3_b32 v4, v0, s9, v3 bitop3:0xde
	v_bitop3_b32 v188, v0, s12, v3 bitop3:0xde
	v_cmp_eq_u32_e64 s[6:7], 0, v1
	v_lshrrev_b32_e32 v1, 1, v9
	v_mul_lo_u32 v0, v11, s8
	s_mov_b32 s0, 0xb000
	v_mad_u64_u32 v[0:1], s[12:13], v1, s0, v[0:1]
	v_or_b32_e32 v0, v0, v10
	v_add_lshl_u32 v162, v0, v12, 1
	v_lshrrev_b32_e32 v1, 1, v13
	v_mul_lo_u32 v0, v14, s8
	v_mad_u64_u32 v[0:1], s[8:9], v1, s0, v[0:1]
	s_waitcnt vmcnt(6)
	v_or_b32_e32 v0, v0, v15
	v_add_lshl_u32 v164, v0, v16, 1
	v_add_u32_e32 v190, s56, v188
	s_add_i32 s53, 0, 0x14000
	v_mbcnt_lo_u32_b32 v0, -1, 0
	s_add_i32 s56, s56, s43
	v_lshl_or_b32 v189, s50, 5, v2
	v_ashrrev_i32_e32 v163, 31, v162
	v_ashrrev_i32_e32 v165, 31, v164
	v_add_u32_e32 v191, 0, v4
	v_add_u32_e32 v192, s53, v188
	s_mov_b64 s[12:13], 0x100
	s_mov_b64 s[14:15], 0x180
	v_mbcnt_hi_u32_b32 v193, -1, v0
	s_add_i32 s54, s46, 0xc000
	s_add_i32 s55, s46, 0xe000
	s_add_i32 s57, s56, 0x2000
	s_mov_b32 s58, 0
	s_barrier
	s_branch .LBB0_350

; #define G_STAGE_A(buf, h, b0, b1, tt) do { const bool _s2 = P::SEG && (tt) >= P::TS; \
;         const char* _g = _s2 ? (b1) + (ptrdiff_t)((tt) - P::TS) * kA2 + (ptrdiff_t)(h) * hA2 : (b0) + (ptrdiff_t)(tt) * kA + (ptrdiff_t)(h) * hA; \
;         stage2(lds + G_SA(buf, h) + ldsw, _g, _s2 ? voA20 : voA0, _s2 ? voA21 : voA1); } while (0)
; #define G_STAGE_B(buf, h, b0, b1, tt) do { const bool _s2 = P::SEG && (tt) >= P::TS; \
;         const char* _g = _s2 ? (b1) + (ptrdiff_t)((tt) - P::TS) * kB2 + (ptrdiff_t)(h) * hB2 : (b0) + (ptrdiff_t)(tt) * kB + (ptrdiff_t)(h) * hB; \
;         stage2(lds + G_SB(buf, h) + ldsw, _g, _s2 ? voB20 : voB0, _s2 ? voB21 : voB1); } while (0)
; #define G_WAIT_V(n) asm volatile("s_waitcnt vmcnt(" #n ")" ::: "memory")
; #define G_BAR __builtin_amdgcn_s_barrier()
;     __device__ __forceinline__ bool unit(int L, Unit& u) const { u.g = L; return order_mn(L, T / 256, NGU / 256, u.pm, u.pn); }
;     __device__ __forceinline__ bool unit(int L, Unit& u) const { u.g = L; return order_mn(L, T / 256, D / 256, u.pm, u.pn); }
;     __device__ __forceinline__ bool unit(int L, Unit& u) const { u.g = 0; return order_mn(L, T / 256, 8, u.pm, u.pn); }
;     __device__ __forceinline__ bool unit(int L, Unit& u) const { if (L >= NG * 8) return false; u.g = L >> 3; u.pm = (L >> 2) & 1; u.pn = L & 3; return true; }
;     ...
;     const char* cA = p.a0(cur); const char* cB = p.b0(cur);
;     const char* cA2 = P::SEG ? p.a1(cur) : cA; const char* cB2 = P::SEG ? p.b1(cur) : cB;
;     G_STAGE_B(0, 0, cB, cB2, 0); G_STAGE_A(0, 0, cA, cA2, 0); G_STAGE_B(0, 1, cB, cB2, 0); G_STAGE_A(0, 1, cA, cA2, 0);
;     if (wr == 1) G_BAR;
;     G_WAIT_V(4); G_BAR;
;     G_STAGE_B(1, 0, cB, cB2, 1); G_STAGE_A(1, 0, cA, cA2, 1); G_STAGE_B(1, 1, cB, cB2, 1);
;     G_WAIT_V(6); G_BAR;
;     __device__ __forceinline__ bool unit(int L, Unit& u) const { if (L >= NG * 4) return false; u.g = L >> 2; u.pm = (L >> 1) & 1; u.pn = L & 1; return true; }
.LBB0_570:
	s_cmp_lt_i32 s74, 5
	s_cselect_b64 s[0:1], -1, 0
	s_cmp_gt_i32 s75, 4
	s_cselect_b64 s[2:3], -1, 0
	s_and_b64 s[0:1], s[0:1], s[2:3]
	s_andn2_b64 vcc, exec, s[0:1]
	s_cbranch_vccnz .LBB0_671
	s_mov_b64 s[0:1], s[72:73]
	v_mov_b32_e32 v0, v220
	s_load_dwordx4 s[8:11], s[0:1], 0x98
	s_add_i32 s0, 0, 0x2080c
	v_mov_b32_e32 v0, s0
	ds_read_b32 v0, v0
	s_movk_i32 s0, 0xff
	s_waitcnt vmcnt(0)
	v_mov_b32_e32 v8, v220
	s_waitcnt lgkmcnt(0)
	v_cmp_lt_i32_e32 vcc, s0, v0
	v_readfirstlane_b32 s33, v0
	v_readfirstlane_b32 s48, v8
	s_cbranch_vccnz .LBB0_585
	v_lshlrev_b32_e32 v0, 4, v8
	v_add_u32_e32 v1, 0x2000, v0
	v_ashrrev_i32_e32 v2, 31, v1
	v_lshrrev_b32_e32 v2, 22, v2
	v_add_u32_e32 v2, v1, v2
	v_ashrrev_i32_e32 v9, 10, v2
	v_mul_i32_i24_e32 v3, 0x400, v9
	v_sub_u32_e32 v1, v1, v3
	v_lshrrev_b32_e32 v3, 4, v1
	v_bitop3_b32 v1, v3, v1, 32 bitop3:0x6c
	v_ashrrev_i32_e32 v3, 31, v1
	v_lshrrev_b32_e32 v3, 26, v3
	v_add_u32_e32 v3, v1, v3
	v_ashrrev_i32_e32 v10, 6, v3
	v_and_b32_e32 v3, 0xc0, v3
	v_sub_u32_e32 v1, v1, v3
	v_mov_b32_e32 v3, 1
	v_lshlrev_b32_e32 v2, 5, v9
	v_ashrrev_i16_sdwa v1, v3, sext(v1) dst_sel:DWORD dst_unused:UNUSED_PAD src0_sel:DWORD src1_sel:BYTE_0
	v_and_b32_e32 v2, 32, v2
	v_bfe_i32 v11, v1, 0, 16
	v_add_u32_e32 v1, v2, v11
	v_lshlrev_b32_e32 v2, 3, v9
	v_and_b32_e32 v2, 0x1ffff0, v2
	v_add_lshl_u32 v2, v10, v2, 11
	v_lshl_add_u32 v128, v1, 1, v2
	v_bfe_i32 v2, v8, 27, 1
	v_lshrrev_b32_e32 v2, 22, v2
	v_add_u32_e32 v2, v0, v2
	v_and_b32_e32 v2, 0xfffffc00, v2
	v_sub_u32_e32 v0, v0, v2
	v_lshrrev_b32_e32 v2, 4, v0
	s_add_u32 s49, s8, 0x6000000
	v_bitop3_b32 v2, v2, v0, 32 bitop3:0x6c
	v_ashrrev_i32_e32 v0, 31, v0
	s_addc_u32 s50, s9, 0
	s_ashr_i32 s0, s33, 2
	v_lshrrev_b32_e32 v0, 26, v0
	s_bfe_u32 s54, s33, 0x10001
	v_ashrrev_i32_e32 v1, 31, v8
	v_add_u32_e32 v0, v2, v0
	s_ashr_i32 s1, s0, 31
	s_and_b32 s53, s33, 1
	v_lshrrev_b32_e32 v1, 26, v1
	v_ashrrev_i32_e32 v13, 6, v0
	s_lshl_b32 s3, s54, 18
	s_lshl_b64 s[6:7], s[0:1], 19
	v_add_u32_e32 v1, v8, v1
	v_mul_i32_i24_e32 v0, 64, v13
	s_or_b32 s1, s6, s3
	s_lshl_b32 s3, s53, 9
	s_ashr_i32 s2, s48, 6
	v_ashrrev_i32_e32 v12, 6, v1
	v_sub_u32_e32 v0, v2, v0
	s_or_b32 s4, s1, s3
	s_mov_b32 s5, s7
	s_ashr_i32 s12, s48, 8
	s_lshl_b32 s51, s2, 10
	v_lshlrev_b32_e32 v1, 5, v12
	v_ashrrev_i16_sdwa v0, v3, sext(v0) dst_sel:DWORD dst_unused:UNUSED_PAD src0_sel:DWORD src1_sel:BYTE_0
	s_lshl_b64 s[4:5], s[4:5], 1
	v_and_b32_e32 v1, 32, v1
	v_bfe_i32 v14, v0, 0, 16
	s_add_u32 s4, s8, s4
	v_add_u32_e32 v0, v1, v14
	v_lshlrev_b32_e32 v1, 3, v12
	s_addc_u32 s5, s9, s5
	s_lshl_b32 s1, s53, 10
	v_and_b32_e32 v1, 0x1ffff0, v1
	s_add_u32 s3, s49, s6
	v_add_lshl_u32 v1, v13, v1, 11
	s_addc_u32 s7, s50, s7
	v_lshl_add_u32 v130, v0, 1, v1
	s_add_u32 s6, s3, s1
	s_addc_u32 s7, s7, 0
	s_add_i32 s52, s51, 0
	v_ashrrev_i32_e32 v131, 31, v130
	s_add_i32 m0, s52, 0x10000
	v_lshl_add_u64 v[0:1], s[6:7], 0, v[130:131]
	v_ashrrev_i32_e32 v129, 31, v128
	global_load_lds_dwordx4 v[0:1], off
	v_lshl_add_u64 v[4:5], s[6:7], 0, v[128:129]
	s_add_i32 m0, s52, 0x12000
	s_add_i32 s55, s52, 0x2000
	global_load_lds_dwordx4 v[4:5], off
	v_lshl_add_u64 v[6:7], s[4:5], 0, v[130:131]
	s_mov_b32 m0, s52
	s_add_u32 s14, s6, 0x40000
	global_load_lds_dwordx4 v[6:7], off
	v_lshl_add_u64 v[2:3], s[4:5], 0, v[128:129]
	s_mov_b32 m0, s55
	s_addc_u32 s15, s7, 0
	global_load_lds_dwordx4 v[2:3], off
	s_add_i32 m0, s52, 0x14000
	v_lshl_add_u64 v[16:17], s[14:15], 0, v[130:131]
	global_load_lds_dwordx4 v[16:17], off
	s_add_i32 m0, s52, 0x16000
	v_lshl_add_u64 v[16:17], s[14:15], 0, v[128:129]
	s_add_u32 s14, s4, 0x40000
	s_addc_u32 s15, s5, 0
	s_add_i32 s56, s52, 0x4000
	global_load_lds_dwordx4 v[16:17], off
	v_lshl_add_u64 v[16:17], s[14:15], 0, v[130:131]
	s_mov_b32 m0, s56
	s_add_i32 s57, s52, 0x6000
	global_load_lds_dwordx4 v[16:17], off
	v_lshl_add_u64 v[16:17], s[14:15], 0, v[128:129]
	s_mov_b32 m0, s57
	global_load_lds_dwordx4 v[16:17], off
	s_movk_i32 s58, 0x4000
	s_lshl_b32 s2, s2, 5
	s_and_b32 s16, s2, 0x60
	s_mov_b64 s[2:3], 0x80
	s_add_i32 m0, s52, 0x18000
	v_lshl_add_u64 v[0:1], v[0:1], 0, s[2:3]
	global_load_lds_dwordx4 v[0:1], off
	v_lshl_add_u64 v[0:1], v[4:5], 0, s[2:3]
	s_add_i32 m0, s52, 0x1a000
	s_add_i32 s61, s52, 0x8000
	s_add_i32 s62, s52, 0xa000
	global_load_lds_dwordx4 v[0:1], off
	v_lshl_add_u64 v[0:1], v[6:7], 0, s[2:3]
	s_mov_b32 m0, s61
	s_add_u32 s14, s6, 0x40080
	global_load_lds_dwordx4 v[0:1], off
	v_lshl_add_u64 v[0:1], v[2:3], 0, s[2:3]
	s_mov_b32 m0, s62
	s_addc_u32 s15, s7, 0
	global_load_lds_dwordx4 v[0:1], off
	s_add_i32 m0, s52, 0x1c000
	v_lshl_add_u64 v[0:1], s[14:15], 0, v[130:131]
	global_load_lds_dwordx4 v[0:1], off
	v_lshl_add_u64 v[0:1], s[14:15], 0, v[128:129]
	s_add_i32 m0, s52, 0x1e000
	s_add_i32 s64, 0, 0x10000
	global_load_lds_dwordx4 v[0:1], off
	s_cmp_lg_u32 s12, 1
	s_cbranch_scc1 .LBB0_574
	s_barrier
.LBB0_574:
	s_add_u32 s59, s10, 0x9400000
	s_addc_u32 s60, s11, 0
	s_lshl_b32 s1, s12, 13
	s_lshl_b32 s13, s16, 7
	s_waitcnt vmcnt(10)
	s_barrier
	v_bfe_u32 v1, v8, 4, 2
	v_and_b32_e32 v0, 15, v8
	v_lshlrev_b32_e32 v2, 4, v1
	v_lshl_or_b32 v142, s12, 6, v0
	v_lshl_or_b32 v0, v0, 6, v2
	v_lshlrev_b32_e32 v2, 2, v8
	v_and_b32_e32 v2, 32, v2
	v_bitop3_b32 v3, v0, s1, v2 bitop3:0xde
	v_bitop3_b32 v143, v0, s13, v2 bitop3:0xde
	v_lshl_or_b32 v0, v1, 2, s16
	v_lshlrev_b32_e32 v1, 14, v12
	v_and_b32_e32 v1, 0xffff8000, v1
	v_lshl_add_u32 v1, v13, 11, v1
	v_and_b32_e32 v2, 1, v12
	v_lshl_or_b32 v1, v2, 6, v1
	v_lshl_add_u32 v134, v14, 1, v1
	v_lshlrev_b32_e32 v1, 14, v9
	v_and_b32_e32 v1, 0xffff8000, v1
	v_lshl_add_u32 v1, v10, 11, v1
	v_and_b32_e32 v2, 1, v9
	s_waitcnt vmcnt(6)
	v_lshl_or_b32 v1, v2, 6, v1
	v_lshl_add_u32 v136, v11, 1, v1
	s_add_i32 s66, 0, 0x14000
	s_mov_b32 s13, 0
	s_mov_b32 s63, 0x8000
	v_mov_b32_e32 v133, 0
	v_ashrrev_i32_e32 v135, 31, v134
	v_ashrrev_i32_e32 v137, 31, v136
	v_add_u32_e32 v144, s64, v143
	v_add_u32_e32 v145, 0, v3
	s_mov_b32 s65, 0xc000
	v_add_u32_e32 v146, s66, v143
	s_mov_b64 s[14:15], 0x100
	s_mov_b64 s[16:17], 0x180
	v_lshlrev_b32_e32 v132, 2, v0
	s_mov_b64 s[18:19], 0x4000
	s_mov_b64 s[20:21], 0x8000
	s_mov_b64 s[22:23], 0xc000
	s_mov_b64 s[24:25], 0x20000
	s_mov_b32 s67, 0x20000
	s_mov_b64 s[26:27], 0x24000
	s_mov_b32 s68, 0x24000
	s_mov_b64 s[28:29], 0x28000
	s_mov_b32 s69, 0x28000
	s_mov_b64 s[30:31], 0x2c000
	s_mov_b32 s70, 0
	s_barrier

; #define G_STAGE_A(buf, h, b0, b1, tt) do { const bool _s2 = P::SEG && (tt) >= P::TS; \
;         const char* _g = _s2 ? (b1) + (ptrdiff_t)((tt) - P::TS) * kA2 + (ptrdiff_t)(h) * hA2 : (b0) + (ptrdiff_t)(tt) * kA + (ptrdiff_t)(h) * hA; \
;         stage2(lds + G_SA(buf, h) + ldsw, _g, _s2 ? voA20 : voA0, _s2 ? voA21 : voA1); } while (0)
; #define G_STAGE_B(buf, h, b0, b1, tt) do { const bool _s2 = P::SEG && (tt) >= P::TS; \
;         const char* _g = _s2 ? (b1) + (ptrdiff_t)((tt) - P::TS) * kB2 + (ptrdiff_t)(h) * hB2 : (b0) + (ptrdiff_t)(tt) * kB + (ptrdiff_t)(h) * hB; \
;         stage2(lds + G_SB(buf, h) + ldsw, _g, _s2 ? voB20 : voB0, _s2 ? voB21 : voB1); } while (0)
; #define G_WAIT_V(n) asm volatile("s_waitcnt vmcnt(" #n ")" ::: "memory")
; #define G_BAR __builtin_amdgcn_s_barrier()
;     ...
;     const char* cA = p.a0(cur); const char* cB = p.b0(cur);
;     const char* cA2 = P::SEG ? p.a1(cur) : cA; const char* cB2 = P::SEG ? p.b1(cur) : cB;
;     G_STAGE_B(0, 0, cB, cB2, 0); G_STAGE_A(0, 0, cA, cA2, 0); G_STAGE_B(0, 1, cB, cB2, 0); G_STAGE_A(0, 1, cA, cA2, 0);
;     if (wr == 1) G_BAR;
;     G_WAIT_V(4); G_BAR;
;     G_STAGE_B(1, 0, cB, cB2, 1); G_STAGE_A(1, 0, cA, cA2, 1); G_STAGE_B(1, 1, cB, cB2, 1);
;     G_WAIT_V(6); G_BAR;
.LBB0_911:
	s_cmp_lt_i32 s74, 8
	s_cselect_b64 s[0:1], -1, 0
	s_cmp_gt_i32 s75, 7
	s_cselect_b64 s[2:3], -1, 0
	s_and_b64 s[0:1], s[0:1], s[2:3]
	s_andn2_b64 vcc, exec, s[0:1]
	s_cbranch_vccnz .LBB0_1026
	s_mov_b64 s[0:1], s[72:73]
	v_mov_b32_e32 v0, v220
	s_load_dwordx2 s[0:1], s[0:1], 0xa0
	s_add_i32 s2, 0, 0x2080c
	v_mov_b32_e32 v0, s2
	ds_read_b32 v0, v0
	s_movk_i32 s2, 0x3ff
	s_waitcnt vmcnt(0)
	v_mov_b32_e32 v9, v220
	s_waitcnt lgkmcnt(0)
	v_cmp_lt_i32_e32 vcc, s2, v0
	v_readfirstlane_b32 s33, v0
	v_readfirstlane_b32 s36, v9
	s_cbranch_vccnz .LBB0_940
	v_lshlrev_b32_e32 v0, 4, v9
	v_add_u32_e32 v1, 0x2000, v0
	v_ashrrev_i32_e32 v2, 31, v1
	v_lshrrev_b32_e32 v2, 22, v2
	v_add_u32_e32 v2, v1, v2
	v_ashrrev_i32_e32 v8, 10, v2
	v_mul_i32_i24_e32 v2, 0x400, v8
	v_sub_u32_e32 v1, v1, v2
	v_lshrrev_b32_e32 v2, 4, v1
	v_bitop3_b32 v1, v2, v1, 32 bitop3:0x6c
	v_ashrrev_i32_e32 v2, 31, v1
	v_lshrrev_b32_e32 v2, 26, v2
	v_add_u32_e32 v2, v1, v2
	v_lshlrev_b32_e32 v3, 3, v8
	v_ashrrev_i32_e32 v10, 6, v2
	v_and_b32_e32 v3, -16, v3
	v_add_u32_e32 v3, v10, v3
	v_and_b32_e32 v4, 3, v10
	s_mov_b32 s2, 0x1fffe0
	v_lshrrev_b32_e32 v5, 2, v3
	v_lshlrev_b32_e32 v6, 1, v3
	v_and_b32_e32 v2, 0xc0, v2
	v_and_or_b32 v4, v3, s2, v4
	v_and_b32_e32 v5, 4, v5
	v_and_b32_e32 v6, 24, v6
	v_sub_u32_e32 v1, v1, v2
	v_mov_b32_e32 v2, 1
	v_or3_b32 v4, v4, v5, v6
	v_lshlrev_b32_e32 v5, 5, v8
	v_ashrrev_i16_sdwa v1, v2, sext(v1) dst_sel:DWORD dst_unused:UNUSED_PAD src0_sel:DWORD src1_sel:BYTE_0
	v_and_b32_e32 v5, 32, v5
	v_bfe_i32 v11, v1, 0, 16
	v_add_lshl_u32 v1, v5, v11, 1
	v_lshl_add_u32 v140, v4, 11, v1
	v_lshl_add_u32 v142, v3, 11, v1
	v_bfe_i32 v1, v9, 27, 1
	v_lshrrev_b32_e32 v1, 22, v1
	v_add_u32_e32 v1, v0, v1
	v_and_b32_e32 v1, 0xfffffc00, v1
	v_sub_u32_e32 v0, v0, v1
	v_lshrrev_b32_e32 v1, 4, v0
	v_bitop3_b32 v1, v1, v0, 32 bitop3:0x6c
	v_ashrrev_i32_e32 v0, 31, v0
	v_lshrrev_b32_e32 v0, 26, v0
	v_add_u32_e32 v0, v1, v0
	v_ashrrev_i32_e32 v12, 6, v0
	v_ashrrev_i32_e32 v0, 31, v9
	v_lshrrev_b32_e32 v0, 26, v0
	v_add_u32_e32 v0, v9, v0
	v_ashrrev_i32_e32 v13, 6, v0
	s_add_u32 s37, s0, 0x7400000
	v_lshlrev_b32_e32 v0, 3, v13
	s_addc_u32 s38, s1, 0
	v_and_b32_e32 v0, -16, v0
	s_add_u32 s39, s0, 0x10080000
	v_add_u32_e32 v0, v12, v0
	v_and_b32_e32 v3, 3, v12
	s_addc_u32 s40, s1, 0
	v_and_or_b32 v3, v0, s2, v3
	s_ashr_i32 s2, s33, 31
	s_lshr_b32 s2, s2, 29
	s_add_i32 s2, s33, s2
	s_ashr_i32 s3, s2, 3
	s_and_b32 s2, s2, -8
	s_sub_i32 s2, s33, s2
	s_lshr_b32 s4, s2, 31
	s_bitset1_b32 s4, 7
	s_mul_i32 s2, s4, s2
	s_add_i32 s2, s2, s3
	v_lshrrev_b32_e32 v4, 2, v0
	v_lshlrev_b32_e32 v5, 1, v0
	s_ashr_i32 s3, s2, 31
	v_and_b32_e32 v4, 4, v4
	v_and_b32_e32 v5, 24, v5
	s_lshr_b32 s3, s3, 26
	v_or3_b32 v3, v3, v4, v5
	v_mul_i32_i24_e32 v5, 64, v12
	s_add_i32 s3, s2, s3
	v_sub_u32_e32 v1, v1, v5
	s_ashr_i32 s4, s3, 6
	v_lshlrev_b32_e32 v4, 5, v13
	v_ashrrev_i16_sdwa v1, v2, sext(v1) dst_sel:DWORD dst_unused:UNUSED_PAD src0_sel:DWORD src1_sel:BYTE_0
	s_lshl_b32 s7, s4, 3
	v_and_b32_e32 v4, 32, v4
	v_bfe_i32 v14, v1, 0, 16
	s_sub_i32 s4, 0x80, s7
	v_add_lshl_u32 v1, v4, v14, 1
	s_min_u32 s8, s4, 8
	s_andn2_b32 s3, s3, 63
	v_lshl_add_u32 v144, v3, 11, v1
	s_sub_i32 s9, s2, s3
	v_cvt_f32_ubyte0_e32 v3, s8
	v_cvt_f32_i32_e32 v2, s9
	v_rcp_iflag_f32_e32 v4, v3
	v_lshl_add_u32 v146, v0, 11, v1
	s_ashr_i32 s6, s36, 6
	s_ashr_i32 s2, s9, 30
	v_mul_f32_e32 v0, v2, v4
	v_trunc_f32_e32 v0, v0
	v_fma_f32 v1, -v0, v3, v2
	v_cvt_i32_f32_e32 v0, v0
	s_ashr_i32 s5, s36, 8
	s_lshl_b32 s14, s6, 10
	s_or_b32 s4, s2, 1
	v_cmp_ge_f32_e64 s[2:3], |v1|, v3
	s_and_b64 s[2:3], s[2:3], exec
	s_cselect_b32 s2, s4, 0
	v_readfirstlane_b32 s3, v0
	s_add_i32 s4, s3, s2
	s_mul_i32 s2, s4, s8
	s_sub_i32 s2, s9, s2
	s_sext_i32_i8 s2, s2
	s_add_i32 s8, s7, s2
	s_ashr_i32 s9, s8, 31
	s_lshl_b64 s[2:3], s[8:9], 19
	s_add_u32 s24, s37, s2
	s_addc_u32 s25, s38, s3
	s_bfe_i64 s[2:3], s[4:5], 0x80000
	s_lshl_b64 s[2:3], s[2:3], 19
	s_add_u32 s26, s39, s2
	s_addc_u32 s27, s40, s3
	s_add_i32 s41, s14, 0
	v_ashrrev_i32_e32 v145, 31, v144
	s_add_i32 m0, s41, 0x10000
	v_lshl_add_u64 v[0:1], s[26:27], 0, v[144:145]
	v_ashrrev_i32_e32 v141, 31, v140
	global_load_lds_dwordx4 v[0:1], off
	v_lshl_add_u64 v[2:3], s[26:27], 0, v[140:141]
	s_add_i32 m0, s41, 0x12000
	v_ashrrev_i32_e32 v147, 31, v146
	s_add_i32 s42, s41, 0x2000
	global_load_lds_dwordx4 v[2:3], off
	v_lshl_add_u64 v[4:5], s[24:25], 0, v[146:147]
	s_mov_b32 m0, s41
	v_ashrrev_i32_e32 v143, 31, v142
	s_add_u32 s2, s26, 0x40000
	global_load_lds_dwordx4 v[4:5], off
	v_lshl_add_u64 v[6:7], s[24:25], 0, v[142:143]
	s_mov_b32 m0, s42
	s_addc_u32 s3, s27, 0
	global_load_lds_dwordx4 v[6:7], off
	s_add_i32 m0, s41, 0x14000
	v_lshl_add_u64 v[16:17], s[2:3], 0, v[144:145]
	global_load_lds_dwordx4 v[16:17], off
	s_add_i32 m0, s41, 0x16000
	v_lshl_add_u64 v[16:17], s[2:3], 0, v[140:141]
	s_add_u32 s2, s24, 0x40000
	s_addc_u32 s3, s25, 0
	s_add_i32 s43, s41, 0x4000
	global_load_lds_dwordx4 v[16:17], off
	v_lshl_add_u64 v[16:17], s[2:3], 0, v[146:147]
	s_mov_b32 m0, s43
	s_add_i32 s44, s41, 0x6000
	global_load_lds_dwordx4 v[16:17], off
	v_lshl_add_u64 v[16:17], s[2:3], 0, v[142:143]
	s_mov_b32 m0, s44
	global_load_lds_dwordx4 v[16:17], off
	s_and_b32 s45, s6, 3
	s_mov_b64 s[6:7], 0x80
	s_add_i32 m0, s41, 0x18000
	v_lshl_add_u64 v[0:1], v[0:1], 0, s[6:7]
	global_load_lds_dwordx4 v[0:1], off
	v_lshl_add_u64 v[0:1], v[2:3], 0, s[6:7]
	s_add_i32 m0, s41, 0x1a000
	s_add_i32 s46, s41, 0x8000
	s_add_i32 s47, s41, 0xa000
	global_load_lds_dwordx4 v[0:1], off
	v_lshl_add_u64 v[0:1], v[4:5], 0, s[6:7]
	s_mov_b32 m0, s46
	s_add_u32 s10, s26, 0x40080
	global_load_lds_dwordx4 v[0:1], off
	v_lshl_add_u64 v[0:1], v[6:7], 0, s[6:7]
	s_mov_b32 m0, s47
	s_addc_u32 s11, s27, 0
	global_load_lds_dwordx4 v[0:1], off
	s_add_i32 m0, s41, 0x1c000
	v_lshl_add_u64 v[0:1], s[10:11], 0, v[144:145]
	global_load_lds_dwordx4 v[0:1], off
	v_lshl_add_u64 v[0:1], s[10:11], 0, v[140:141]
	s_add_i32 m0, s41, 0x1e000
	s_sext_i32_i8 s59, s4
	global_load_lds_dwordx4 v[0:1], off
	s_cmp_lg_u32 s5, 1
	s_cbranch_scc1 .LBB0_915
	s_barrier
; #define G_STAGE_A(buf, h, b0, b1, tt) do { const bool _s2 = P::SEG && (tt) >= P::TS; \
;         const char* _g = _s2 ? (b1) + (ptrdiff_t)((tt) - P::TS) * kA2 + (ptrdiff_t)(h) * hA2 : (b0) + (ptrdiff_t)(tt) * kA + (ptrdiff_t)(h) * hA; \
;         stage2(lds + G_SA(buf, h) + ldsw, _g, _s2 ? voA20 : voA0, _s2 ? voA21 : voA1); } while (0)
; #define G_STAGE_B(buf, h, b0, b1, tt) do { const bool _s2 = P::SEG && (tt) >= P::TS; \
;         const char* _g = _s2 ? (b1) + (ptrdiff_t)((tt) - P::TS) * kB2 + (ptrdiff_t)(h) * hB2 : (b0) + (ptrdiff_t)(tt) * kB + (ptrdiff_t)(h) * hB; \
;         stage2(lds + G_SB(buf, h) + ldsw, _g, _s2 ? voB20 : voB0, _s2 ? voB21 : voB1); } while (0)
; #define G_WAIT_V(n) asm volatile("s_waitcnt vmcnt(" #n ")" ::: "memory")
; #define G_BAR __builtin_amdgcn_s_barrier()
;     ...
;     const unsigned ldsw = (unsigned)wid * 1024u;
;     const int aoff = lds_byte(wr * 64 + fr, fq * 8), boff = lds_byte(wc * 32 + fr, fq * 8);
;     ...
;     G_WAIT_V(4); G_BAR;
;     G_STAGE_B(1, 0, cB, cB2, 1); G_STAGE_A(1, 0, cA, cA2, 1); G_STAGE_B(1, 1, cB, cB2, 1);
;     G_WAIT_V(6); G_BAR;
.LBB0_915:
	s_add_u32 s2, s0, 0x10500000
	s_addc_u32 s3, s1, 0
	s_lshl_b32 s9, s5, 13
	s_lshl_b32 s12, s45, 12
	s_waitcnt vmcnt(10)
	s_barrier
	v_and_b32_e32 v0, 15, v9
	v_bfe_u32 v1, v9, 4, 2
	v_lshl_or_b32 v170, s5, 6, v0
	v_lshlrev_b32_e32 v2, 3, v1
	v_lshlrev_b32_e32 v3, 4, v1
	v_cmp_eq_u32_e64 s[4:5], 0, v1
	v_lshlrev_b32_e32 v1, 14, v13
	v_and_b32_e32 v1, 0xffff8000, v1
	v_lshl_or_b32 v171, s45, 5, v2
	v_lshl_add_u32 v1, v12, 11, v1
	v_and_b32_e32 v2, 1, v13
	v_lshl_or_b32 v1, v2, 6, v1
	v_lshl_add_u32 v148, v14, 1, v1
	v_lshlrev_b32_e32 v1, 14, v8
	v_lshl_or_b32 v0, v0, 6, v3
	v_lshlrev_b32_e32 v3, 2, v9
	v_and_b32_e32 v1, 0xffff8000, v1
	v_and_b32_e32 v3, 32, v3
	v_lshl_add_u32 v1, v10, 11, v1
	v_and_b32_e32 v2, 1, v8
	v_bitop3_b32 v4, v0, s9, v3 bitop3:0xde
	v_bitop3_b32 v0, v0, s12, v3 bitop3:0xde
	s_waitcnt vmcnt(6)
	v_lshl_or_b32 v1, v2, 6, v1
	s_add_i32 s50, 0, 0x10000
	s_add_i32 s52, 0, 0x14000
	s_add_i32 s54, 0, 0x18000
	s_add_i32 s56, 0, 0x1c000
	v_lshl_add_u32 v150, v11, 1, v1
	v_add_u32_e32 v172, s50, v0
	v_add_u32_e32 v174, s52, v0
	v_mbcnt_lo_u32_b32 v1, -1, 0
	s_add_i32 s50, s50, s14
	s_add_i32 s52, s52, s14
	v_add_u32_e32 v176, s54, v0
	v_add_u32_e32 v177, s56, v0
	s_add_i32 s54, s54, s14
	s_add_i32 s56, s56, s14
	s_mov_b32 s9, 0
	v_ashrrev_i32_e32 v149, 31, v148
	v_ashrrev_i32_e32 v151, 31, v150
	v_add_u32_e32 v173, 0, v4
	s_add_i32 s48, s41, 0xc000
	s_add_i32 s49, s41, 0xe000
	s_mov_b64 s[10:11], 0x100
	s_mov_b64 s[12:13], 0x180
	v_mbcnt_hi_u32_b32 v175, -1, v1
	s_add_i32 s51, s50, 0x2000
	s_add_i32 s53, s52, 0x2000
	s_add_i32 s55, s54, 0x2000
	s_add_i32 s57, s56, 0x2000
	s_mov_b32 s58, 0
	s_barrier
	s_branch .LBB0_917

; #define G_STAGE_A(buf, h, b0, b1, tt) do { const bool _s2 = P::SEG && (tt) >= P::TS; \
;         const char* _g = _s2 ? (b1) + (ptrdiff_t)((tt) - P::TS) * kA2 + (ptrdiff_t)(h) * hA2 : (b0) + (ptrdiff_t)(tt) * kA + (ptrdiff_t)(h) * hA; \
;         stage2(lds + G_SA(buf, h) + ldsw, _g, _s2 ? voA20 : voA0, _s2 ? voA21 : voA1); } while (0)
; #define G_STAGE_B(buf, h, b0, b1, tt) do { const bool _s2 = P::SEG && (tt) >= P::TS; \
;         const char* _g = _s2 ? (b1) + (ptrdiff_t)((tt) - P::TS) * kB2 + (ptrdiff_t)(h) * hB2 : (b0) + (ptrdiff_t)(tt) * kB + (ptrdiff_t)(h) * hB; \
;         stage2(lds + G_SB(buf, h) + ldsw, _g, _s2 ? voB20 : voB0, _s2 ? voB21 : voB1); } while (0)
; #define G_WAIT_V(n) asm volatile("s_waitcnt vmcnt(" #n ")" ::: "memory")
; #define G_BAR __builtin_amdgcn_s_barrier()
;     ...
;     const char* cA = p.a0(cur); const char* cB = p.b0(cur);
;     const char* cA2 = P::SEG ? p.a1(cur) : cA; const char* cB2 = P::SEG ? p.b1(cur) : cB;
;     G_STAGE_B(0, 0, cB, cB2, 0); G_STAGE_A(0, 0, cA, cA2, 0); G_STAGE_B(0, 1, cB, cB2, 0); G_STAGE_A(0, 1, cA, cA2, 0);
;     if (wr == 1) G_BAR;
;     G_WAIT_V(4); G_BAR;
;     G_STAGE_B(1, 0, cB, cB2, 1); G_STAGE_A(1, 0, cA, cA2, 1); G_STAGE_B(1, 1, cB, cB2, 1);
;     G_WAIT_V(6); G_BAR;
.LBB0_1660:
	s_cmp_lt_i32 s74, 15
	s_cselect_b64 s[0:1], -1, 0
	s_cmp_gt_i32 s75, 14
	s_cselect_b64 s[2:3], -1, 0
	s_and_b64 s[0:1], s[0:1], s[2:3]
	s_andn2_b64 vcc, exec, s[0:1]
	s_cbranch_vccnz .LBB0_1775
	s_mov_b64 s[0:1], s[72:73]
	v_mov_b32_e32 v0, v220
	s_load_dwordx2 s[0:1], s[0:1], 0xa0
	s_add_i32 s2, 0, 0x2080c
	v_mov_b32_e32 v0, s2
	ds_read_b32 v0, v0
	s_movk_i32 s2, 0x1ff
	s_waitcnt vmcnt(0)
	v_mov_b32_e32 v8, v220
	s_waitcnt lgkmcnt(0)
	v_cmp_lt_i32_e32 vcc, s2, v0
	v_readfirstlane_b32 s30, v0
	v_readfirstlane_b32 s31, v8
	s_cbranch_vccnz .LBB0_1689
	v_lshlrev_b32_e32 v0, 4, v8
	v_add_u32_e32 v1, 0x2000, v0
	v_ashrrev_i32_e32 v2, 31, v1
	v_lshrrev_b32_e32 v2, 22, v2
	v_add_u32_e32 v2, v1, v2
	v_ashrrev_i32_e32 v2, 10, v2
	v_mul_i32_i24_e32 v3, 0x400, v2
	v_sub_u32_e32 v1, v1, v3
	v_lshrrev_b32_e32 v3, 4, v1
	v_bitop3_b32 v1, v3, v1, 32 bitop3:0x6c
	v_ashrrev_i32_e32 v3, 31, v1
	v_lshrrev_b32_e32 v3, 26, v3
	v_add_u32_e32 v3, v1, v3
	v_lshlrev_b32_e32 v5, 3, v2
	v_ashrrev_i32_e32 v4, 6, v3
	v_and_b32_e32 v5, -16, v5
	v_and_b32_e32 v3, 0xc0, v3
	v_add_u32_e32 v5, v4, v5
	v_sub_u32_e32 v1, v1, v3
	v_mov_b32_e32 v3, 1
	v_and_b32_e32 v4, 3, v4
	s_mov_b32 s2, 0x7fffe0
	v_lshrrev_b32_e32 v6, 2, v5
	v_lshlrev_b32_e32 v7, 1, v5
	v_lshlrev_b32_e32 v2, 5, v2
	v_ashrrev_i16_sdwa v1, v3, sext(v1) dst_sel:DWORD dst_unused:UNUSED_PAD src0_sel:DWORD src1_sel:BYTE_0
	v_and_or_b32 v4, v5, s2, v4
	v_and_b32_e32 v6, 4, v6
	v_and_b32_e32 v7, 24, v7
	v_and_b32_e32 v2, 32, v2
	v_bfe_i32 v1, v1, 0, 16
	v_or3_b32 v4, v4, v6, v7
	v_add_lshl_u32 v1, v2, v1, 1
	v_lshl_add_u32 v144, v4, 9, v1
	v_lshl_add_u32 v146, v5, 11, v1
	v_bfe_i32 v1, v8, 27, 1
	v_lshrrev_b32_e32 v1, 22, v1
	v_add_u32_e32 v1, v0, v1
	v_and_b32_e32 v1, 0xfffffc00, v1
	v_sub_u32_e32 v0, v0, v1
	v_ashrrev_i32_e32 v2, 31, v8
	v_lshrrev_b32_e32 v1, 4, v0
	v_lshrrev_b32_e32 v2, 26, v2
	v_bitop3_b32 v1, v1, v0, 32 bitop3:0x6c
	v_ashrrev_i32_e32 v0, 31, v0
	v_add_u32_e32 v2, v8, v2
	v_lshrrev_b32_e32 v0, 26, v0
	v_ashrrev_i32_e32 v2, 6, v2
	s_add_u32 s33, s0, 0x4000000
	v_add_u32_e32 v0, v1, v0
	v_lshlrev_b32_e32 v4, 3, v2
	s_addc_u32 s34, s1, 0
	v_ashrrev_i32_e32 v0, 6, v0
	v_and_b32_e32 v4, -16, v4
	s_add_u32 s35, s0, 0x10480000
	v_add_u32_e32 v4, v0, v4
	v_and_b32_e32 v5, 3, v0
	s_addc_u32 s36, s1, 0
	v_and_or_b32 v5, v4, s2, v5
	s_ashr_i32 s2, s30, 31
	s_lshr_b32 s2, s2, 29
	s_add_i32 s2, s30, s2
	s_ashr_i32 s3, s2, 3
	s_and_b32 s2, s2, -8
	s_sub_i32 s2, s30, s2
	s_lshr_b32 s4, s2, 31
	s_or_b32 s4, s4, 64
	s_mul_i32 s2, s4, s2
	s_add_i32 s2, s2, s3
	s_ashr_i32 s3, s2, 31
	s_lshr_b32 s3, s3, 27
	s_add_i32 s3, s2, s3
	v_mul_i32_i24_e32 v0, 64, v0
	s_ashr_i32 s4, s3, 5
	v_sub_u32_e32 v0, v1, v0
	s_lshl_b32 s7, s4, 3
	v_lshlrev_b32_e32 v2, 5, v2
	v_ashrrev_i16_sdwa v0, v3, sext(v0) dst_sel:DWORD dst_unused:UNUSED_PAD src0_sel:DWORD src1_sel:BYTE_0
	s_sub_i32 s4, 0x80, s7
	v_and_b32_e32 v2, 32, v2
	v_bfe_i32 v0, v0, 0, 16
	s_min_u32 s8, s4, 8
	s_andn2_b32 s3, s3, 31
	v_add_lshl_u32 v0, v2, v0, 1
	s_sub_i32 s9, s2, s3
	v_cvt_f32_ubyte0_e32 v2, s8
	v_cvt_f32_i32_e32 v1, s9
	v_rcp_iflag_f32_e32 v3, v2
	v_lshrrev_b32_e32 v6, 2, v4
	v_lshlrev_b32_e32 v7, 1, v4
	v_and_b32_e32 v6, 4, v6
	v_and_b32_e32 v7, 24, v7
	v_or3_b32 v5, v5, v6, v7
	v_lshl_add_u32 v148, v5, 9, v0
	v_lshl_add_u32 v150, v4, 11, v0
	v_mul_f32_e32 v0, v1, v3
	v_trunc_f32_e32 v0, v0
	v_fma_f32 v1, -v0, v2, v1
	v_cvt_i32_f32_e32 v0, v0
	s_ashr_i32 s6, s31, 6
	s_ashr_i32 s2, s9, 30
	s_ashr_i32 s5, s31, 8
	s_lshl_b32 s37, s6, 10
	s_or_b32 s4, s2, 1
	v_cmp_ge_f32_e64 s[2:3], |v1|, v2
	s_and_b64 s[2:3], s[2:3], exec
	s_cselect_b32 s2, s4, 0
	v_readfirstlane_b32 s3, v0
	s_add_i32 s4, s3, s2
	s_mul_i32 s2, s4, s8
	s_sub_i32 s2, s9, s2
	s_sext_i32_i8 s2, s2
	s_add_i32 s8, s7, s2
	s_bfe_i64 s[2:3], s[4:5], 0x80000
	s_ashr_i32 s9, s8, 31
	s_lshl_b64 s[10:11], s[2:3], 9
	s_lshl_b64 s[12:13], s[8:9], 19
	s_add_u32 s7, s33, s12
	s_addc_u32 s9, s34, s13
	s_add_u32 s24, s7, s10
	s_addc_u32 s25, s9, s11
	s_lshl_b64 s[2:3], s[2:3], 17
	s_add_u32 s26, s35, s2
	s_addc_u32 s27, s36, s3
	s_add_i32 s38, s37, 0
	v_ashrrev_i32_e32 v149, 31, v148
	s_add_i32 m0, s38, 0x10000
	v_lshl_add_u64 v[0:1], s[26:27], 0, v[148:149]
	v_ashrrev_i32_e32 v145, 31, v144
	global_load_lds_dwordx4 v[0:1], off
	v_lshl_add_u64 v[2:3], s[26:27], 0, v[144:145]
	s_add_i32 m0, s38, 0x12000
	v_ashrrev_i32_e32 v151, 31, v150
	s_add_i32 s39, s38, 0x2000
	global_load_lds_dwordx4 v[2:3], off
	v_lshl_add_u64 v[4:5], s[24:25], 0, v[150:151]
	s_mov_b32 m0, s38
	v_ashrrev_i32_e32 v147, 31, v146
	s_add_u32 s2, s26, 0x10000
	global_load_lds_dwordx4 v[4:5], off
	v_lshl_add_u64 v[6:7], s[24:25], 0, v[146:147]
	s_mov_b32 m0, s39
	s_addc_u32 s3, s27, 0
	global_load_lds_dwordx4 v[6:7], off
	s_add_i32 m0, s38, 0x14000
	v_lshl_add_u64 v[10:11], s[2:3], 0, v[148:149]
	global_load_lds_dwordx4 v[10:11], off
	s_add_i32 m0, s38, 0x16000
	v_lshl_add_u64 v[10:11], s[2:3], 0, v[144:145]
	s_add_u32 s2, s24, 0x40000
	s_addc_u32 s3, s25, 0
	s_add_i32 s40, s38, 0x4000
	global_load_lds_dwordx4 v[10:11], off
	v_lshl_add_u64 v[10:11], s[2:3], 0, v[150:151]
	s_mov_b32 m0, s40
	s_add_i32 s41, s38, 0x6000
	global_load_lds_dwordx4 v[10:11], off
	v_lshl_add_u64 v[10:11], s[2:3], 0, v[146:147]
	s_mov_b32 m0, s41
	global_load_lds_dwordx4 v[10:11], off
	s_and_b32 s42, s6, 3
	s_mov_b64 s[6:7], 0x80
	s_add_i32 m0, s38, 0x18000
	v_lshl_add_u64 v[0:1], v[0:1], 0, s[6:7]
	global_load_lds_dwordx4 v[0:1], off
	v_lshl_add_u64 v[0:1], v[2:3], 0, s[6:7]
	s_add_i32 m0, s38, 0x1a000
	s_add_i32 s43, s38, 0x8000
	s_add_i32 s44, s38, 0xa000
	global_load_lds_dwordx4 v[0:1], off
	v_lshl_add_u64 v[0:1], v[4:5], 0, s[6:7]
	s_mov_b32 m0, s43
	s_add_u32 s10, s26, 0x10080
	global_load_lds_dwordx4 v[0:1], off
	v_lshl_add_u64 v[0:1], v[6:7], 0, s[6:7]
	s_mov_b32 m0, s44
	s_addc_u32 s11, s27, 0
	global_load_lds_dwordx4 v[0:1], off
	s_add_i32 m0, s38, 0x1c000
	v_lshl_add_u64 v[0:1], s[10:11], 0, v[148:149]
	global_load_lds_dwordx4 v[0:1], off
	v_lshl_add_u64 v[0:1], s[10:11], 0, v[144:145]
	s_add_i32 m0, s38, 0x1e000
	s_add_i32 s49, 0, 0x10000
	global_load_lds_dwordx4 v[0:1], off
	s_cmp_lg_u32 s5, 1
	s_cbranch_scc1 .LBB0_1664
	s_barrier
; #define G_STAGE_A(buf, h, b0, b1, tt) do { const bool _s2 = P::SEG && (tt) >= P::TS; \
;         const char* _g = _s2 ? (b1) + (ptrdiff_t)((tt) - P::TS) * kA2 + (ptrdiff_t)(h) * hA2 : (b0) + (ptrdiff_t)(tt) * kA + (ptrdiff_t)(h) * hA; \
;         stage2(lds + G_SA(buf, h) + ldsw, _g, _s2 ? voA20 : voA0, _s2 ? voA21 : voA1); } while (0)
; #define G_STAGE_B(buf, h, b0, b1, tt) do { const bool _s2 = P::SEG && (tt) >= P::TS; \
;         const char* _g = _s2 ? (b1) + (ptrdiff_t)((tt) - P::TS) * kB2 + (ptrdiff_t)(h) * hB2 : (b0) + (ptrdiff_t)(tt) * kB + (ptrdiff_t)(h) * hB; \
;         stage2(lds + G_SB(buf, h) + ldsw, _g, _s2 ? voB20 : voB0, _s2 ? voB21 : voB1); } while (0)
; #define G_WAIT_V(n) asm volatile("s_waitcnt vmcnt(" #n ")" ::: "memory")
; #define G_BAR __builtin_amdgcn_s_barrier()
;     ...
;     const unsigned ldsw = (unsigned)wid * 1024u;
;     const int aoff = lds_byte(wr * 64 + fr, fq * 8), boff = lds_byte(wc * 32 + fr, fq * 8);
;     ...
;     G_WAIT_V(4); G_BAR;
;     G_STAGE_B(1, 0, cB, cB2, 1); G_STAGE_A(1, 0, cA, cA2, 1); G_STAGE_B(1, 1, cB, cB2, 1);
;     G_WAIT_V(6); G_BAR;
.LBB0_1664:
	s_add_u32 s2, s0, 0x10500000
	s_addc_u32 s3, s1, 0
	s_lshl_b32 s9, s5, 13
	s_lshl_b32 s12, s42, 12
	s_waitcnt vmcnt(10)
	s_barrier
	v_bfe_u32 v1, v8, 4, 2
	v_and_b32_e32 v0, 15, v8
	v_lshlrev_b32_e32 v3, 4, v1
	v_lshl_or_b32 v170, s5, 6, v0
	v_lshl_or_b32 v0, v0, 6, v3
	v_lshlrev_b32_e32 v3, 2, v8
	v_and_b32_e32 v3, 32, v3
	v_bitop3_b32 v4, v0, s9, v3 bitop3:0xde
	v_bitop3_b32 v171, v0, s12, v3 bitop3:0xde
	v_mbcnt_lo_u32_b32 v0, -1, 0
	s_waitcnt vmcnt(6)
	v_mbcnt_hi_u32_b32 v176, -1, v0
	v_lshlrev_b32_e32 v2, 3, v1
	v_add_u32_e32 v173, s49, v171
	s_add_i32 s46, 0, 0x14000
	v_and_b32_e32 v0, 64, v176
	s_add_i32 s49, s49, s37
	s_sext_i32_i8 s45, s4
	s_mov_b32 s9, 0
	v_lshl_or_b32 v172, s42, 5, v2
	v_cmp_eq_u32_e64 s[4:5], 0, v1
	v_add_u32_e32 v174, 0, v4
	v_add_u32_e32 v175, s46, v171
	s_mov_b64 s[10:11], 0x100
	s_mov_b64 s[12:13], 0x180
	v_xor_b32_e32 v177, 16, v176
	v_add_u32_e32 v178, 64, v0
	v_xor_b32_e32 v179, 32, v176
	s_add_i32 s47, s38, 0xc000
	s_add_i32 s48, s38, 0xe000
	s_add_i32 s50, s49, 0x2000
	s_barrier
	s_branch .LBB0_1666

; #define G_STAGE_A(buf, h, b0, b1, tt) do { const bool _s2 = P::SEG && (tt) >= P::TS; \
;         const char* _g = _s2 ? (b1) + (ptrdiff_t)((tt) - P::TS) * kA2 + (ptrdiff_t)(h) * hA2 : (b0) + (ptrdiff_t)(tt) * kA + (ptrdiff_t)(h) * hA; \
;         stage2(lds + G_SA(buf, h) + ldsw, _g, _s2 ? voA20 : voA0, _s2 ? voA21 : voA1); } while (0)
; #define G_STAGE_B(buf, h, b0, b1, tt) do { const bool _s2 = P::SEG && (tt) >= P::TS; \
;         const char* _g = _s2 ? (b1) + (ptrdiff_t)((tt) - P::TS) * kB2 + (ptrdiff_t)(h) * hB2 : (b0) + (ptrdiff_t)(tt) * kB + (ptrdiff_t)(h) * hB; \
;         stage2(lds + G_SB(buf, h) + ldsw, _g, _s2 ? voB20 : voB0, _s2 ? voB21 : voB1); } while (0)
; #define G_WAIT_V(n) asm volatile("s_waitcnt vmcnt(" #n ")" ::: "memory")
; #define G_BAR __builtin_amdgcn_s_barrier()
;     __device__ __forceinline__ int voffA(int R, int C) const { return (R * LDA + C) * 2; }
;     __device__ __forceinline__ int voffB(int R, int C) const { return (R * LDB + C) * 2; }
;     __device__ __forceinline__ int voffA(int R, int C) const { return (R * D + C) * 2; }
;     __device__ __forceinline__ int voffB(int R, int C) const { return (((R >> 4) - (C >> 4)) * 256 + (R & 15) * 16 + (C & 15)) * 2; }
;     __device__ __forceinline__ int voffA2(int R, int C) const { return (R * 256 + C) * 2; }
;     __device__ __forceinline__ int voffB2(int R, int C) const { return (R * 256 + C) * 2; }
;     ...
;     { int R, C; stage_rc(tid * 16, R, C); int Rb = P::PERM ? ((R & ~31) + perm32(R & 31)) : R; voA0 = p.voffA(R, C); voB0 = p.voffB(Rb, C);
;       if constexpr (P::SEG) { voA20 = p.voffA2(R, C); voB20 = p.voffB2(Rb, C); } }
;     { int R, C; stage_rc(tid * 16 + 8192, R, C); int Rb = P::PERM ? ((R & ~31) + perm32(R & 31)) : R; voA1 = p.voffA(R, C); voB1 = p.voffB(Rb, C);
;       if constexpr (P::SEG) { voA21 = p.voffA2(R, C); voB21 = p.voffB2(Rb, C); } }
;     ...
;     const char* cA = p.a0(cur); const char* cB = p.b0(cur);
;     const char* cA2 = P::SEG ? p.a1(cur) : cA; const char* cB2 = P::SEG ? p.b1(cur) : cB;
;     G_STAGE_B(0, 0, cB, cB2, 0); G_STAGE_A(0, 0, cA, cA2, 0); G_STAGE_B(0, 1, cB, cB2, 0); G_STAGE_A(0, 1, cA, cA2, 0);
;     if (wr == 1) G_BAR;
;     G_WAIT_V(4); G_BAR;
;     G_STAGE_B(1, 0, cB, cB2, 1); G_STAGE_A(1, 0, cA, cA2, 1); G_STAGE_B(1, 1, cB, cB2, 1);
;     G_WAIT_V(6); G_BAR;
.LBB0_1895:
	v_ashrrev_i32_e32 v1, 31, v8
	v_lshrrev_b32_e32 v1, 26, v1
	v_add_u32_e32 v1, v8, v1
	v_ashrrev_i32_e32 v9, 6, v1
	v_bfe_i32 v1, v8, 27, 1
	v_lshlrev_b32_e32 v0, 4, v8
	v_lshrrev_b32_e32 v1, 22, v1
	v_add_u32_e32 v1, v0, v1
	v_and_b32_e32 v1, 0xfffffc00, v1
	v_sub_u32_e32 v1, v0, v1
	v_lshrrev_b32_e32 v2, 4, v1
	v_bitop3_b32 v2, v2, v1, 32 bitop3:0x6c
	v_ashrrev_i32_e32 v1, 31, v1
	v_lshrrev_b32_e32 v1, 26, v1
	v_lshlrev_b32_e32 v3, 3, v9
	v_add_u32_e32 v1, v2, v1
	v_and_b32_e32 v3, -16, v3
	v_ashrrev_i32_e32 v11, 6, v1
	v_add_u32_e32 v1, v11, v3
	v_lshlrev_b32_e32 v3, 5, v9
	v_and_b32_e32 v10, 32, v3
	v_mul_i32_i24_e32 v3, 64, v11
	v_sub_u32_e32 v2, v2, v3
	v_mov_b32_e32 v3, 1
	v_ashrrev_i16_sdwa v2, v3, sext(v2) dst_sel:DWORD dst_unused:UNUSED_PAD src0_sel:DWORD src1_sel:BYTE_0
	v_lshlrev_b32_e32 v4, 1, v1
	v_lshrrev_b32_e32 v5, 2, v1
	v_and_b32_e32 v6, 3, v11
	s_mov_b32 s3, 0xffffe0
	v_bfe_i32 v12, v2, 0, 16
	v_and_b32_e32 v4, 24, v4
	v_and_b32_e32 v5, 4, v5
	v_and_or_b32 v6, v1, s3, v6
	s_movk_i32 s6, 0xb00
	v_add_u32_e32 v2, v10, v12
	v_or3_b32 v4, v6, v5, v4
	v_mul_lo_u32 v1, v1, s6
	v_add_lshl_u32 v152, v2, v1, 1
	v_mul_u32_u24_e32 v1, 0xb00, v4
	v_add_u32_e32 v0, 0x2000, v0
	v_add_lshl_u32 v154, v1, v2, 1
	v_ashrrev_i32_e32 v1, 31, v0
	v_lshrrev_b32_e32 v1, 22, v1
	v_add_u32_e32 v1, v0, v1
	v_ashrrev_i32_e32 v13, 10, v1
	v_mul_i32_i24_e32 v1, 0x400, v13
	v_sub_u32_e32 v0, v0, v1
	v_lshrrev_b32_e32 v1, 4, v0
	v_bitop3_b32 v0, v1, v0, 32 bitop3:0x6c
	v_ashrrev_i32_e32 v2, 31, v0
	s_add_u32 s31, s0, 0x4000000
	v_lshrrev_b32_e32 v2, 26, v2
	s_addc_u32 s33, s1, 0
	v_lshlrev_b32_e32 v1, 3, v13
	v_add_u32_e32 v2, v0, v2
	s_add_u32 s34, s0, 0xfb00000
	v_and_b32_e32 v1, -16, v1
	v_ashrrev_i32_e32 v14, 6, v2
	v_and_b32_e32 v2, 0xc0, v2
	s_addc_u32 s35, s1, 0
	s_ashr_i32 s5, s29, 6
	v_add_u32_e32 v1, v14, v1
	v_lshlrev_b32_e32 v4, 5, v13
	v_sub_u32_e32 v0, v0, v2
	s_ashr_i32 s4, s29, 8
	v_and_b32_e32 v15, 32, v4
	v_ashrrev_i16_sdwa v0, v3, sext(v0) dst_sel:DWORD dst_unused:UNUSED_PAD src0_sel:DWORD src1_sel:BYTE_0
	v_lshlrev_b32_e32 v2, 1, v1
	v_lshrrev_b32_e32 v3, 2, v1
	v_and_b32_e32 v4, 3, v14
	s_lshl_b32 s36, s5, 10
	s_mul_i32 s7, s2, 0x160000
	v_bfe_i32 v16, v0, 0, 16
	v_and_b32_e32 v2, 24, v2
	v_and_b32_e32 v3, 4, v3
	v_and_or_b32 v4, v1, s3, v4
	s_mul_hi_i32 s3, s2, 0x160000
	s_add_u32 s20, s31, s7
	v_add_u32_e32 v0, v15, v16
	v_or3_b32 v2, v4, v3, v2
	v_mul_lo_u32 v1, v1, s6
	s_addc_u32 s21, s33, s3
	s_mul_i32 s7, s30, 0x160000
	v_add_lshl_u32 v156, v0, v1, 1
	v_mul_u32_u24_e32 v1, 0xb00, v2
	s_mul_hi_i32 s3, s30, 0x160000
	s_add_u32 s22, s34, s7
	v_add_lshl_u32 v158, v1, v0, 1
	s_addc_u32 s23, s35, s3
	s_add_i32 s37, s36, 0
	v_ashrrev_i32_e32 v155, 31, v154
	s_add_i32 m0, s37, 0x10000
	v_lshl_add_u64 v[0:1], s[22:23], 0, v[154:155]
	v_ashrrev_i32_e32 v159, 31, v158
	global_load_lds_dwordx4 v[0:1], off
	v_lshl_add_u64 v[2:3], s[22:23], 0, v[158:159]
	s_add_i32 m0, s37, 0x12000
	v_ashrrev_i32_e32 v153, 31, v152
	s_add_i32 s38, s37, 0x2000
	global_load_lds_dwordx4 v[2:3], off
	v_lshl_add_u64 v[4:5], s[20:21], 0, v[152:153]
	s_mov_b32 m0, s37
	v_ashrrev_i32_e32 v157, 31, v156
	s_add_u32 s8, s22, 0xb0000
	global_load_lds_dwordx4 v[4:5], off
	v_lshl_add_u64 v[6:7], s[20:21], 0, v[156:157]
	s_mov_b32 m0, s38
	s_addc_u32 s9, s23, 0
	global_load_lds_dwordx4 v[6:7], off
	s_add_i32 m0, s37, 0x14000
	v_lshl_add_u64 v[18:19], s[8:9], 0, v[154:155]
	global_load_lds_dwordx4 v[18:19], off
	s_add_i32 m0, s37, 0x16000
	v_lshl_add_u64 v[18:19], s[8:9], 0, v[158:159]
	s_add_u32 s8, s20, 0xb0000
	s_addc_u32 s9, s21, 0
	s_add_i32 s39, s37, 0x4000
	global_load_lds_dwordx4 v[18:19], off
	v_lshl_add_u64 v[18:19], s[8:9], 0, v[152:153]
	s_mov_b32 m0, s39
	s_add_i32 s40, s37, 0x6000
	global_load_lds_dwordx4 v[18:19], off
	v_lshl_add_u64 v[18:19], s[8:9], 0, v[156:157]
	s_mov_b32 m0, s40
	global_load_lds_dwordx4 v[18:19], off
	s_mov_b32 s3, 0
	s_mov_b64 s[10:11], 0x80
	s_add_i32 m0, s37, 0x18000
	v_lshl_add_u64 v[0:1], v[0:1], 0, s[10:11]
	global_load_lds_dwordx4 v[0:1], off
	v_lshl_add_u64 v[0:1], v[2:3], 0, s[10:11]
	s_add_i32 m0, s37, 0x1a000
	s_add_i32 s42, s37, 0x8000
	s_add_i32 s43, s37, 0xa000
	global_load_lds_dwordx4 v[0:1], off
	v_lshl_add_u64 v[0:1], v[4:5], 0, s[10:11]
	s_mov_b32 m0, s42
	s_add_u32 s12, s22, 0xb0080
	global_load_lds_dwordx4 v[0:1], off
	v_lshl_add_u64 v[0:1], v[6:7], 0, s[10:11]
	s_mov_b32 m0, s43
	s_addc_u32 s13, s23, 0
	global_load_lds_dwordx4 v[0:1], off
	s_add_i32 m0, s37, 0x1c000
	v_lshl_add_u64 v[0:1], s[12:13], 0, v[154:155]
	global_load_lds_dwordx4 v[0:1], off
	v_lshl_add_u64 v[0:1], s[12:13], 0, v[158:159]
	s_add_i32 m0, s37, 0x1e000
	s_add_i32 s47, 0, 0x10000
	global_load_lds_dwordx4 v[0:1], off
	s_cmp_lg_u32 s4, 1
	s_cbranch_scc1 .LBB0_1897
	s_barrier
.LBB0_1897:
	s_add_u32 s8, s0, 0x10500000
	s_addc_u32 s9, s1, 0
	s_and_b32 s41, s5, 3
	s_lshl_b32 s5, s4, 13
	s_lshl_b32 s7, s41, 12
	s_waitcnt vmcnt(10)
	s_barrier
	v_bfe_u32 v1, v8, 4, 2
	v_and_b32_e32 v0, 15, v8
	v_lshlrev_b32_e32 v3, 4, v1
	v_lshl_or_b32 v182, s4, 6, v0
	v_lshl_or_b32 v0, v0, 6, v3
	v_lshlrev_b32_e32 v3, 2, v8
	v_and_b32_e32 v3, 32, v3
	v_lshlrev_b32_e32 v2, 3, v1
	v_bitop3_b32 v4, v0, s5, v3 bitop3:0xde
	v_bitop3_b32 v183, v0, s7, v3 bitop3:0xde
	v_cmp_eq_u32_e64 s[4:5], 0, v1
	v_lshrrev_b32_e32 v1, 1, v9
	v_mul_lo_u32 v0, v11, s6
	s_mov_b32 s7, 0xb000
	v_mad_u64_u32 v[0:1], s[12:13], v1, s7, v[0:1]
	v_or_b32_e32 v0, v0, v10
	v_add_lshl_u32 v160, v0, v12, 1
	v_lshrrev_b32_e32 v1, 1, v13
	v_mul_lo_u32 v0, v14, s6
	v_mad_u64_u32 v[0:1], s[6:7], v1, s7, v[0:1]
	s_waitcnt vmcnt(6)
	v_or_b32_e32 v0, v0, v15
	v_add_lshl_u32 v162, v0, v16, 1
	v_add_u32_e32 v185, s47, v183
	s_add_i32 s44, 0, 0x14000
	v_mbcnt_lo_u32_b32 v0, -1, 0
	s_add_i32 s47, s47, s36
	v_lshl_or_b32 v184, s41, 5, v2
	v_ashrrev_i32_e32 v161, 31, v160
	v_ashrrev_i32_e32 v163, 31, v162
	v_add_u32_e32 v186, 0, v4
	v_add_u32_e32 v187, s44, v183
	s_mov_b64 s[12:13], 0x100
	s_mov_b64 s[14:15], 0x180
	v_mbcnt_hi_u32_b32 v188, -1, v0
	s_add_i32 s45, s37, 0xc000
	s_add_i32 s46, s37, 0xe000
	s_add_i32 s48, s47, 0x2000
	s_mov_b32 s49, 0
	s_barrier
	s_branch .LBB0_1899
